# dil_merge loop: loads of 4 items issued together (was two exposed memory latencies per item)
# baseline (speedup 1.0000x reference)
; DI float bflo(unsigned u) { return __uint_as_float(u << 16); }
; DI float bfhi(unsigned u) { return __uint_as_float(u & 0xffff0000u); }
; DI void dil_merge(const Ctx& c) {
;     { const bf16_t* DP = BIGP(bf16_t, B_DILP); const float* DM = BIGP(float, B_DILM); bf16_t* OD = BIGP(bf16_t, B_ONA) + 256;
;         for (int it = c.bid * 512 + c.tid; it < c.stok * 32; it += c.G * 512) { const int tok = it >> 5, part = it & 31;
;             u32x4 w = {0u, 0u, 0u, 0u};
;             if (part < 16) { const int hd = part >> 3, p = part & 7; float m[3], dn[3];
; #pragma unroll
;                 for (int g = 0; g < 3; ++g) { const size_t b = (((size_t)g * SLABMAX + tok) * 2 + hd); m[g] = DM[b * 2]; dn[g] = DM[b * 2 + 1]; }
;                 const float M = fmaxf(m[0], fmaxf(m[1], m[2])); float num[8], den = 0.f;
; #pragma unroll
;                 for (int j = 0; j < 8; ++j) num[j] = 0.f;
; #pragma unroll
;                 for (int g = 0; g < 3; ++g) { const float f = __expf(m[g] - M); den += f * dn[g]; const u32x4 a = *(const u32x4*)(DP + (((size_t)g * SLABMAX + tok) * 2 + hd) * 64 + 8 * p);
;                     num[0] += f * bflo(a[0]); num[1] += f * bfhi(a[0]); num[2] += f * bflo(a[1]); num[3] += f * bfhi(a[1]); num[4] += f * bflo(a[2]); num[5] += f * bfhi(a[2]); num[6] += f * bflo(a[3]); num[7] += f * bfhi(a[3]); }
.LBB0_997:
	s_andn2_b64 vcc, exec, s[0:1]
	s_cbranch_vccnz .LBB0_1054
	v_mov_b32_e32 v1, v0
	s_mov_b64 s[6:7], s[80:81]
	s_load_dwordx2 s[2:3], s[6:7], 0xa8
	s_mov_b32 s20, s79
	s_mov_b32 s21, s78
	s_lshl_b32 s23, s41, 5
	v_lshl_add_u32 v23, s21, 9, v1
	v_readfirstlane_b32 s22, v1
	v_cmp_gt_i32_e32 vcc, s23, v23
	v_lshlrev_b32_e32 v22, 3, v1
	v_and_b32_e32 v21, 31, v1
	s_and_saveexec_b64 s[0:1], vcc
	s_cbranch_execz .LBB0_1003
	s_waitcnt lgkmcnt(0)
	s_add_u32 s8, s2, 0x35e00000
	s_addc_u32 s9, s3, 0
	s_add_u32 s10, s2, 0x37600000
	s_addc_u32 s11, s3, 0
	s_add_u32 s12, s2, 0x37680000
	s_addc_u32 s13, s3, 0
	v_lshlrev_b32_e32 v2, 4, v21
	s_add_u32 s14, s2, 0x37700000
	v_lshl_add_u64 v[4:5], s[2:3], 0, v[2:3]
	s_mov_b64 s[4:5], 0x32600200
	s_addc_u32 s15, s3, 0
	s_lshl_b32 s24, s20, 9
	v_cmp_gt_u32_e32 vcc, 16, v21
	v_and_b32_e32 v12, 0x80, v2
	v_mov_b32_e32 v13, v3
	v_lshl_add_u64 v[14:15], v[4:5], 0, s[4:5]
	v_lshl_add_u32 v24, s21, 12, v22
	s_lshl_b32 s25, s20, 12
	s_and_saveexec_b64 s[18:19], vcc
	s_lshl_b32 s16, s21, 9
.Ldm_trip:
	v_ashrrev_i32_e32 v190, 5, v23
	v_ashrrev_i32_e32 v191, 31, v190
	v_lshlrev_b64 v[4:5], 4, v[190:191]
	v_and_or_b32 v4, v23, 24, v4
	v_lshl_add_u64 v[6:7], s[10:11], 0, v[4:5]
	v_lshl_add_u64 v[8:9], s[12:13], 0, v[4:5]
	v_lshl_add_u64 v[4:5], s[14:15], 0, v[4:5]
	global_load_dwordx2 v[114:115], v[6:7], off
	global_load_dwordx2 v[116:117], v[8:9], off
	global_load_dwordx2 v[118:119], v[4:5], off
	v_and_b32_e32 v2, 7, v23
	v_lshlrev_b32_e32 v2, 4, v2
	v_lshl_add_u64 v[4:5], s[8:9], 0, v[2:3]
	v_lshlrev_b64 v[6:7], 8, v[190:191]
	v_lshl_add_u64 v[4:5], v[4:5], 0, v[6:7]
	v_lshl_add_u64 v[30:31], v[4:5], 0, v[12:13]
	s_mov_b64 s[4:5], 0x800000
	v_lshl_add_u64 v[4:5], v[30:31], 0, s[4:5]
	s_mov_b64 s[4:5], 0x1000000
	v_lshl_add_u64 v[8:9], v[30:31], 0, s[4:5]
	global_load_dwordx4 v[120:123], v[30:31], off
	global_load_dwordx4 v[124:127], v[4:5], off
	global_load_dwordx4 v[128:131], v[8:9], off
	s_add_i32 s17, s16, s24
	s_cmp_lt_i32 s17, s23
	s_cbranch_scc0 .Ldm_tail
	v_add_u32_e32 v187, s24, v23
	v_ashrrev_i32_e32 v192, 5, v187
	v_ashrrev_i32_e32 v193, 31, v192
	v_lshlrev_b64 v[4:5], 4, v[192:193]
	v_and_or_b32 v4, v187, 24, v4
	v_lshl_add_u64 v[6:7], s[10:11], 0, v[4:5]
	v_lshl_add_u64 v[8:9], s[12:13], 0, v[4:5]
	v_lshl_add_u64 v[4:5], s[14:15], 0, v[4:5]
	global_load_dwordx2 v[132:133], v[6:7], off
	global_load_dwordx2 v[134:135], v[8:9], off
	global_load_dwordx2 v[136:137], v[4:5], off
	v_and_b32_e32 v2, 7, v187
	v_lshlrev_b32_e32 v2, 4, v2
	v_lshl_add_u64 v[4:5], s[8:9], 0, v[2:3]
	v_lshlrev_b64 v[6:7], 8, v[192:193]
	v_lshl_add_u64 v[4:5], v[4:5], 0, v[6:7]
	v_lshl_add_u64 v[30:31], v[4:5], 0, v[12:13]
	s_mov_b64 s[4:5], 0x800000
	v_lshl_add_u64 v[4:5], v[30:31], 0, s[4:5]
	s_mov_b64 s[4:5], 0x1000000
	v_lshl_add_u64 v[8:9], v[30:31], 0, s[4:5]
	global_load_dwordx4 v[138:141], v[30:31], off
	global_load_dwordx4 v[142:145], v[4:5], off
	global_load_dwordx4 v[146:149], v[8:9], off
	s_add_i32 s17, s17, s24
	s_cmp_lt_i32 s17, s23
	s_cbranch_scc0 .Ldm_tail
	v_add_u32_e32 v188, s24, v187
	v_ashrrev_i32_e32 v194, 5, v188
	v_ashrrev_i32_e32 v195, 31, v194
	v_lshlrev_b64 v[4:5], 4, v[194:195]
	v_and_or_b32 v4, v188, 24, v4
	v_lshl_add_u64 v[6:7], s[10:11], 0, v[4:5]
	v_lshl_add_u64 v[8:9], s[12:13], 0, v[4:5]
	v_lshl_add_u64 v[4:5], s[14:15], 0, v[4:5]
	global_load_dwordx2 v[150:151], v[6:7], off
	global_load_dwordx2 v[152:153], v[8:9], off
	global_load_dwordx2 v[154:155], v[4:5], off
	v_and_b32_e32 v2, 7, v188
	v_lshlrev_b32_e32 v2, 4, v2
	v_lshl_add_u64 v[4:5], s[8:9], 0, v[2:3]
	v_lshlrev_b64 v[6:7], 8, v[194:195]
	v_lshl_add_u64 v[4:5], v[4:5], 0, v[6:7]
	v_lshl_add_u64 v[30:31], v[4:5], 0, v[12:13]
	s_mov_b64 s[4:5], 0x800000
	v_lshl_add_u64 v[4:5], v[30:31], 0, s[4:5]
	s_mov_b64 s[4:5], 0x1000000
	v_lshl_add_u64 v[8:9], v[30:31], 0, s[4:5]
	global_load_dwordx4 v[156:159], v[30:31], off
	global_load_dwordx4 v[160:163], v[4:5], off
	global_load_dwordx4 v[164:167], v[8:9], off
	s_add_i32 s17, s17, s24
	s_cmp_lt_i32 s17, s23
	s_cbranch_scc0 .Ldm_tail
	v_add_u32_e32 v189, s24, v188
	v_ashrrev_i32_e32 v196, 5, v189
	v_ashrrev_i32_e32 v197, 31, v196
	v_lshlrev_b64 v[4:5], 4, v[196:197]
	v_and_or_b32 v4, v189, 24, v4
	v_lshl_add_u64 v[6:7], s[10:11], 0, v[4:5]
	v_lshl_add_u64 v[8:9], s[12:13], 0, v[4:5]
	v_lshl_add_u64 v[4:5], s[14:15], 0, v[4:5]
	global_load_dwordx2 v[168:169], v[6:7], off
	global_load_dwordx2 v[170:171], v[8:9], off
	global_load_dwordx2 v[172:173], v[4:5], off
	v_and_b32_e32 v2, 7, v189
	v_lshlrev_b32_e32 v2, 4, v2
	v_lshl_add_u64 v[4:5], s[8:9], 0, v[2:3]
	v_lshlrev_b64 v[6:7], 8, v[196:197]
	v_lshl_add_u64 v[4:5], v[4:5], 0, v[6:7]
	v_lshl_add_u64 v[30:31], v[4:5], 0, v[12:13]
	s_mov_b64 s[4:5], 0x800000
	v_lshl_add_u64 v[4:5], v[30:31], 0, s[4:5]
	s_mov_b64 s[4:5], 0x1000000
	v_lshl_add_u64 v[8:9], v[30:31], 0, s[4:5]
	global_load_dwordx4 v[174:177], v[30:31], off
	global_load_dwordx4 v[178:181], v[4:5], off
	global_load_dwordx4 v[182:185], v[8:9], off
	s_branch .Ldm_compute

; DI unsigned pk2(float lo, float hi) { f32x2 v = {lo, hi}; bf16x2v b = __builtin_convertvector(v, bf16x2v); return __builtin_bit_cast(unsigned, b); }
; DI float bflo(unsigned u) { return __uint_as_float(u << 16); }
; DI float bfhi(unsigned u) { return __uint_as_float(u & 0xffff0000u); }
; DI float frcp(float x) { return __builtin_amdgcn_rcpf(x); }
; DI void dil_merge(const Ctx& c) {
;     ...
;         for (int it = c.bid * 512 + c.tid; it < c.stok * 32; it += c.G * 512) { const int tok = it >> 5, part = it & 31;
;             u32x4 w = {0u, 0u, 0u, 0u};
;             if (part < 16) { const int hd = part >> 3, p = part & 7; float m[3], dn[3];
; #pragma unroll
;                 for (int g = 0; g < 3; ++g) { const size_t b = (((size_t)g * SLABMAX + tok) * 2 + hd); m[g] = DM[b * 2]; dn[g] = DM[b * 2 + 1]; }
;                 const float M = fmaxf(m[0], fmaxf(m[1], m[2])); float num[8], den = 0.f;
; #pragma unroll
;                 for (int j = 0; j < 8; ++j) num[j] = 0.f;
; #pragma unroll
;                 for (int g = 0; g < 3; ++g) { const float f = __expf(m[g] - M); den += f * dn[g]; const u32x4 a = *(const u32x4*)(DP + (((size_t)g * SLABMAX + tok) * 2 + hd) * 64 + 8 * p);
;                     num[0] += f * bflo(a[0]); num[1] += f * bfhi(a[0]); num[2] += f * bflo(a[1]); num[3] += f * bfhi(a[1]); num[4] += f * bflo(a[2]); num[5] += f * bfhi(a[2]); num[6] += f * bflo(a[3]); num[7] += f * bfhi(a[3]); }
;                 const float inv = frcp(den);
;                 w.x = pk2(num[0] * inv, num[1] * inv); w.y = pk2(num[2] * inv, num[3] * inv); w.z = pk2(num[4] * inv, num[5] * inv); w.w = pk2(num[6] * inv, num[7] * inv); }
;             if (part < 16) *(u32x4*)(OD + (size_t)tok * 768 + 8 * part) = w; } }
.Ldm_compute:
	s_waitcnt vmcnt(18)
	v_max3_f32 v18, v114, v116, v118
	v_sub_f32_e32 v2, v114, v18
	v_mul_f32_e32 v2, 0x3fb8aa3b, v2
	v_exp_f32_e32 v20, v2
	s_nop 0
	v_fma_f32 v2, v115, v20, 0
	v_sub_f32_e32 v4, v116, v18
	v_sub_f32_e32 v8, v118, v18
	v_mul_f32_e32 v4, 0x3fb8aa3b, v4
	v_mul_f32_e32 v8, 0x3fb8aa3b, v8
	v_exp_f32_e32 v19, v4
	v_exp_f32_e32 v18, v8
	v_mov_b32_e32 v8, v119
	v_mov_b32_e32 v9, v117
	s_nop 0
	v_pk_mul_f32 v[8:9], v[8:9], v[18:19]
	v_add_f32_e32 v2, v9, v2
	v_add_f32_e32 v2, v8, v2
	v_rcp_f32_e32 v2, v2
	v_mov_b32_e32 v26, v19
	v_lshlrev_b32_e32 v30, 16, v120
	v_and_b32_e32 v31, 0xffff0000, v120
	v_pk_fma_f32 v[30:31], v[20:21], v[30:31], 0 op_sel_hi:[0,1,0]
	v_lshlrev_b32_e32 v32, 16, v124
	v_and_b32_e32 v33, 0xffff0000, v124
	v_pk_fma_f32 v[30:31], v[26:27], v[32:33], v[30:31] op_sel_hi:[0,1,1]
	v_lshlrev_b32_e32 v32, 16, v128
	v_and_b32_e32 v33, 0xffff0000, v128
	v_pk_fma_f32 v[30:31], v[18:19], v[32:33], v[30:31] op_sel_hi:[0,1,1]
	v_pk_mul_f32 v[30:31], v[30:31], v[2:3] op_sel_hi:[1,0]
	s_nop 0
	v_cvt_pk_bf16_f32 v4, v30, v31
	v_lshlrev_b32_e32 v30, 16, v121
	v_and_b32_e32 v31, 0xffff0000, v121
	v_pk_fma_f32 v[30:31], v[20:21], v[30:31], 0 op_sel_hi:[0,1,0]
	v_lshlrev_b32_e32 v32, 16, v125
	v_and_b32_e32 v33, 0xffff0000, v125
	v_pk_fma_f32 v[30:31], v[26:27], v[32:33], v[30:31] op_sel_hi:[0,1,1]
	v_lshlrev_b32_e32 v32, 16, v129
	v_and_b32_e32 v33, 0xffff0000, v129
	v_pk_fma_f32 v[30:31], v[18:19], v[32:33], v[30:31] op_sel_hi:[0,1,1]
	v_pk_mul_f32 v[30:31], v[30:31], v[2:3] op_sel_hi:[1,0]
	s_nop 0
	v_cvt_pk_bf16_f32 v5, v30, v31
	v_lshlrev_b32_e32 v30, 16, v122
	v_and_b32_e32 v31, 0xffff0000, v122
	v_pk_fma_f32 v[30:31], v[20:21], v[30:31], 0 op_sel_hi:[0,1,0]
	v_lshlrev_b32_e32 v32, 16, v126
	v_and_b32_e32 v33, 0xffff0000, v126
	v_pk_fma_f32 v[30:31], v[26:27], v[32:33], v[30:31] op_sel_hi:[0,1,1]
	v_lshlrev_b32_e32 v32, 16, v130
	v_and_b32_e32 v33, 0xffff0000, v130
	v_pk_fma_f32 v[30:31], v[18:19], v[32:33], v[30:31] op_sel_hi:[0,1,1]
	v_pk_mul_f32 v[30:31], v[30:31], v[2:3] op_sel_hi:[1,0]
	s_nop 0
	v_cvt_pk_bf16_f32 v6, v30, v31
	v_lshlrev_b32_e32 v30, 16, v123
	v_and_b32_e32 v31, 0xffff0000, v123
	v_pk_fma_f32 v[30:31], v[20:21], v[30:31], 0 op_sel_hi:[0,1,0]
	v_lshlrev_b32_e32 v32, 16, v127
	v_and_b32_e32 v33, 0xffff0000, v127
	v_pk_fma_f32 v[30:31], v[26:27], v[32:33], v[30:31] op_sel_hi:[0,1,1]
	v_lshlrev_b32_e32 v32, 16, v131
	v_and_b32_e32 v33, 0xffff0000, v131
	v_pk_fma_f32 v[30:31], v[18:19], v[32:33], v[30:31] op_sel_hi:[0,1,1]
	v_pk_mul_f32 v[30:31], v[30:31], v[2:3] op_sel_hi:[1,0]
	s_nop 0
	v_cvt_pk_bf16_f32 v7, v30, v31
	v_mad_i64_i32 v[8:9], s[4:5], v190, s71, v[14:15]
	global_store_dwordx4 v[8:9], v[4:7], off
	s_add_i32 s17, s16, s24
	s_cmp_lt_i32 s17, s23
	s_cbranch_scc0 .Ldm_done
	s_waitcnt vmcnt(13)
	v_max3_f32 v18, v132, v134, v136
	v_sub_f32_e32 v2, v132, v18
	v_mul_f32_e32 v2, 0x3fb8aa3b, v2
	v_exp_f32_e32 v20, v2
	s_nop 0
	v_fma_f32 v2, v133, v20, 0
	v_sub_f32_e32 v4, v134, v18
	v_sub_f32_e32 v8, v136, v18
	v_mul_f32_e32 v4, 0x3fb8aa3b, v4
	v_mul_f32_e32 v8, 0x3fb8aa3b, v8
	v_exp_f32_e32 v19, v4
	v_exp_f32_e32 v18, v8
	v_mov_b32_e32 v8, v137
	v_mov_b32_e32 v9, v135
	s_nop 0
	v_pk_mul_f32 v[8:9], v[8:9], v[18:19]
	v_add_f32_e32 v2, v9, v2
	v_add_f32_e32 v2, v8, v2
	v_rcp_f32_e32 v2, v2
	v_mov_b32_e32 v26, v19
	v_lshlrev_b32_e32 v30, 16, v138
	v_and_b32_e32 v31, 0xffff0000, v138
	v_pk_fma_f32 v[30:31], v[20:21], v[30:31], 0 op_sel_hi:[0,1,0]
	v_lshlrev_b32_e32 v32, 16, v142
	v_and_b32_e32 v33, 0xffff0000, v142
	v_pk_fma_f32 v[30:31], v[26:27], v[32:33], v[30:31] op_sel_hi:[0,1,1]
	v_lshlrev_b32_e32 v32, 16, v146
	v_and_b32_e32 v33, 0xffff0000, v146
	v_pk_fma_f32 v[30:31], v[18:19], v[32:33], v[30:31] op_sel_hi:[0,1,1]
	v_pk_mul_f32 v[30:31], v[30:31], v[2:3] op_sel_hi:[1,0]
	s_nop 0
	v_cvt_pk_bf16_f32 v4, v30, v31
	v_lshlrev_b32_e32 v30, 16, v139
	v_and_b32_e32 v31, 0xffff0000, v139
	v_pk_fma_f32 v[30:31], v[20:21], v[30:31], 0 op_sel_hi:[0,1,0]
	v_lshlrev_b32_e32 v32, 16, v143
	v_and_b32_e32 v33, 0xffff0000, v143
	v_pk_fma_f32 v[30:31], v[26:27], v[32:33], v[30:31] op_sel_hi:[0,1,1]
	v_lshlrev_b32_e32 v32, 16, v147
	v_and_b32_e32 v33, 0xffff0000, v147
	v_pk_fma_f32 v[30:31], v[18:19], v[32:33], v[30:31] op_sel_hi:[0,1,1]
	v_pk_mul_f32 v[30:31], v[30:31], v[2:3] op_sel_hi:[1,0]
	s_nop 0
	v_cvt_pk_bf16_f32 v5, v30, v31
	v_lshlrev_b32_e32 v30, 16, v140
	v_and_b32_e32 v31, 0xffff0000, v140
	v_pk_fma_f32 v[30:31], v[20:21], v[30:31], 0 op_sel_hi:[0,1,0]
	v_lshlrev_b32_e32 v32, 16, v144
	v_and_b32_e32 v33, 0xffff0000, v144
	v_pk_fma_f32 v[30:31], v[26:27], v[32:33], v[30:31] op_sel_hi:[0,1,1]
	v_lshlrev_b32_e32 v32, 16, v148
	v_and_b32_e32 v33, 0xffff0000, v148
	v_pk_fma_f32 v[30:31], v[18:19], v[32:33], v[30:31] op_sel_hi:[0,1,1]
	v_pk_mul_f32 v[30:31], v[30:31], v[2:3] op_sel_hi:[1,0]
	s_nop 0
	v_cvt_pk_bf16_f32 v6, v30, v31
	v_lshlrev_b32_e32 v30, 16, v141
	v_and_b32_e32 v31, 0xffff0000, v141
	v_pk_fma_f32 v[30:31], v[20:21], v[30:31], 0 op_sel_hi:[0,1,0]
	v_lshlrev_b32_e32 v32, 16, v145
	v_and_b32_e32 v33, 0xffff0000, v145
	v_pk_fma_f32 v[30:31], v[26:27], v[32:33], v[30:31] op_sel_hi:[0,1,1]
	v_lshlrev_b32_e32 v32, 16, v149
	v_and_b32_e32 v33, 0xffff0000, v149
	v_pk_fma_f32 v[30:31], v[18:19], v[32:33], v[30:31] op_sel_hi:[0,1,1]
	v_pk_mul_f32 v[30:31], v[30:31], v[2:3] op_sel_hi:[1,0]
	s_nop 0
	v_cvt_pk_bf16_f32 v7, v30, v31
	v_mad_i64_i32 v[8:9], s[4:5], v192, s71, v[14:15]
	global_store_dwordx4 v[8:9], v[4:7], off
	s_add_i32 s17, s17, s24
	s_cmp_lt_i32 s17, s23
	s_cbranch_scc0 .Ldm_done
; DI unsigned pk2(float lo, float hi) { f32x2 v = {lo, hi}; bf16x2v b = __builtin_convertvector(v, bf16x2v); return __builtin_bit_cast(unsigned, b); }
; DI float bflo(unsigned u) { return __uint_as_float(u << 16); }
; DI float bfhi(unsigned u) { return __uint_as_float(u & 0xffff0000u); }
; DI float frcp(float x) { return __builtin_amdgcn_rcpf(x); }
; DI void dil_merge(const Ctx& c) {
;     ...
;         for (int it = c.bid * 512 + c.tid; it < c.stok * 32; it += c.G * 512) { const int tok = it >> 5, part = it & 31;
;             u32x4 w = {0u, 0u, 0u, 0u};
;             if (part < 16) { const int hd = part >> 3, p = part & 7; float m[3], dn[3];
; #pragma unroll
;                 for (int g = 0; g < 3; ++g) { const size_t b = (((size_t)g * SLABMAX + tok) * 2 + hd); m[g] = DM[b * 2]; dn[g] = DM[b * 2 + 1]; }
;                 const float M = fmaxf(m[0], fmaxf(m[1], m[2])); float num[8], den = 0.f;
; #pragma unroll
;                 for (int j = 0; j < 8; ++j) num[j] = 0.f;
; #pragma unroll
;                 for (int g = 0; g < 3; ++g) { const float f = __expf(m[g] - M); den += f * dn[g]; const u32x4 a = *(const u32x4*)(DP + (((size_t)g * SLABMAX + tok) * 2 + hd) * 64 + 8 * p);
;                     num[0] += f * bflo(a[0]); num[1] += f * bfhi(a[0]); num[2] += f * bflo(a[1]); num[3] += f * bfhi(a[1]); num[4] += f * bflo(a[2]); num[5] += f * bfhi(a[2]); num[6] += f * bflo(a[3]); num[7] += f * bfhi(a[3]); }
;                 const float inv = frcp(den);
;                 w.x = pk2(num[0] * inv, num[1] * inv); w.y = pk2(num[2] * inv, num[3] * inv); w.z = pk2(num[4] * inv, num[5] * inv); w.w = pk2(num[6] * inv, num[7] * inv); }
;             if (part < 16) *(u32x4*)(OD + (size_t)tok * 768 + 8 * part) = w; } }
	s_waitcnt vmcnt(8)
	v_max3_f32 v18, v150, v152, v154
	v_sub_f32_e32 v2, v150, v18
	v_mul_f32_e32 v2, 0x3fb8aa3b, v2
	v_exp_f32_e32 v20, v2
	s_nop 0
	v_fma_f32 v2, v151, v20, 0
	v_sub_f32_e32 v4, v152, v18
	v_sub_f32_e32 v8, v154, v18
	v_mul_f32_e32 v4, 0x3fb8aa3b, v4
	v_mul_f32_e32 v8, 0x3fb8aa3b, v8
	v_exp_f32_e32 v19, v4
	v_exp_f32_e32 v18, v8
	v_mov_b32_e32 v8, v155
	v_mov_b32_e32 v9, v153
	s_nop 0
	v_pk_mul_f32 v[8:9], v[8:9], v[18:19]
	v_add_f32_e32 v2, v9, v2
	v_add_f32_e32 v2, v8, v2
	v_rcp_f32_e32 v2, v2
	v_mov_b32_e32 v26, v19
	v_lshlrev_b32_e32 v30, 16, v156
	v_and_b32_e32 v31, 0xffff0000, v156
	v_pk_fma_f32 v[30:31], v[20:21], v[30:31], 0 op_sel_hi:[0,1,0]
	v_lshlrev_b32_e32 v32, 16, v160
	v_and_b32_e32 v33, 0xffff0000, v160
	v_pk_fma_f32 v[30:31], v[26:27], v[32:33], v[30:31] op_sel_hi:[0,1,1]
	v_lshlrev_b32_e32 v32, 16, v164
	v_and_b32_e32 v33, 0xffff0000, v164
	v_pk_fma_f32 v[30:31], v[18:19], v[32:33], v[30:31] op_sel_hi:[0,1,1]
	v_pk_mul_f32 v[30:31], v[30:31], v[2:3] op_sel_hi:[1,0]
	s_nop 0
	v_cvt_pk_bf16_f32 v4, v30, v31
	v_lshlrev_b32_e32 v30, 16, v157
	v_and_b32_e32 v31, 0xffff0000, v157
	v_pk_fma_f32 v[30:31], v[20:21], v[30:31], 0 op_sel_hi:[0,1,0]
	v_lshlrev_b32_e32 v32, 16, v161
	v_and_b32_e32 v33, 0xffff0000, v161
	v_pk_fma_f32 v[30:31], v[26:27], v[32:33], v[30:31] op_sel_hi:[0,1,1]
	v_lshlrev_b32_e32 v32, 16, v165
	v_and_b32_e32 v33, 0xffff0000, v165
	v_pk_fma_f32 v[30:31], v[18:19], v[32:33], v[30:31] op_sel_hi:[0,1,1]
	v_pk_mul_f32 v[30:31], v[30:31], v[2:3] op_sel_hi:[1,0]
	s_nop 0
	v_cvt_pk_bf16_f32 v5, v30, v31
	v_lshlrev_b32_e32 v30, 16, v158
	v_and_b32_e32 v31, 0xffff0000, v158
	v_pk_fma_f32 v[30:31], v[20:21], v[30:31], 0 op_sel_hi:[0,1,0]
	v_lshlrev_b32_e32 v32, 16, v162
	v_and_b32_e32 v33, 0xffff0000, v162
	v_pk_fma_f32 v[30:31], v[26:27], v[32:33], v[30:31] op_sel_hi:[0,1,1]
	v_lshlrev_b32_e32 v32, 16, v166
	v_and_b32_e32 v33, 0xffff0000, v166
	v_pk_fma_f32 v[30:31], v[18:19], v[32:33], v[30:31] op_sel_hi:[0,1,1]
	v_pk_mul_f32 v[30:31], v[30:31], v[2:3] op_sel_hi:[1,0]
	s_nop 0
	v_cvt_pk_bf16_f32 v6, v30, v31
	v_lshlrev_b32_e32 v30, 16, v159
	v_and_b32_e32 v31, 0xffff0000, v159
	v_pk_fma_f32 v[30:31], v[20:21], v[30:31], 0 op_sel_hi:[0,1,0]
	v_lshlrev_b32_e32 v32, 16, v163
	v_and_b32_e32 v33, 0xffff0000, v163
	v_pk_fma_f32 v[30:31], v[26:27], v[32:33], v[30:31] op_sel_hi:[0,1,1]
	v_lshlrev_b32_e32 v32, 16, v167
	v_and_b32_e32 v33, 0xffff0000, v167
	v_pk_fma_f32 v[30:31], v[18:19], v[32:33], v[30:31] op_sel_hi:[0,1,1]
	v_pk_mul_f32 v[30:31], v[30:31], v[2:3] op_sel_hi:[1,0]
	s_nop 0
	v_cvt_pk_bf16_f32 v7, v30, v31
	v_mad_i64_i32 v[8:9], s[4:5], v194, s71, v[14:15]
	global_store_dwordx4 v[8:9], v[4:7], off
	s_add_i32 s17, s17, s24
	s_cmp_lt_i32 s17, s23
	s_cbranch_scc0 .Ldm_done
	s_waitcnt vmcnt(3)
	v_max3_f32 v18, v168, v170, v172
	v_sub_f32_e32 v2, v168, v18
	v_mul_f32_e32 v2, 0x3fb8aa3b, v2
	v_exp_f32_e32 v20, v2
	s_nop 0
	v_fma_f32 v2, v169, v20, 0
	v_sub_f32_e32 v4, v170, v18
	v_sub_f32_e32 v8, v172, v18
	v_mul_f32_e32 v4, 0x3fb8aa3b, v4
	v_mul_f32_e32 v8, 0x3fb8aa3b, v8
	v_exp_f32_e32 v19, v4
	v_exp_f32_e32 v18, v8
	v_mov_b32_e32 v8, v173
	v_mov_b32_e32 v9, v171
	s_nop 0
	v_pk_mul_f32 v[8:9], v[8:9], v[18:19]
	v_add_f32_e32 v2, v9, v2
	v_add_f32_e32 v2, v8, v2
	v_rcp_f32_e32 v2, v2
	v_mov_b32_e32 v26, v19
	v_lshlrev_b32_e32 v30, 16, v174
	v_and_b32_e32 v31, 0xffff0000, v174
	v_pk_fma_f32 v[30:31], v[20:21], v[30:31], 0 op_sel_hi:[0,1,0]
	v_lshlrev_b32_e32 v32, 16, v178
	v_and_b32_e32 v33, 0xffff0000, v178
	v_pk_fma_f32 v[30:31], v[26:27], v[32:33], v[30:31] op_sel_hi:[0,1,1]
	v_lshlrev_b32_e32 v32, 16, v182
	v_and_b32_e32 v33, 0xffff0000, v182
	v_pk_fma_f32 v[30:31], v[18:19], v[32:33], v[30:31] op_sel_hi:[0,1,1]
	v_pk_mul_f32 v[30:31], v[30:31], v[2:3] op_sel_hi:[1,0]
	s_nop 0
	v_cvt_pk_bf16_f32 v4, v30, v31
	v_lshlrev_b32_e32 v30, 16, v175
	v_and_b32_e32 v31, 0xffff0000, v175
	v_pk_fma_f32 v[30:31], v[20:21], v[30:31], 0 op_sel_hi:[0,1,0]
	v_lshlrev_b32_e32 v32, 16, v179
	v_and_b32_e32 v33, 0xffff0000, v179
	v_pk_fma_f32 v[30:31], v[26:27], v[32:33], v[30:31] op_sel_hi:[0,1,1]
	v_lshlrev_b32_e32 v32, 16, v183
	v_and_b32_e32 v33, 0xffff0000, v183
	v_pk_fma_f32 v[30:31], v[18:19], v[32:33], v[30:31] op_sel_hi:[0,1,1]
	v_pk_mul_f32 v[30:31], v[30:31], v[2:3] op_sel_hi:[1,0]
	s_nop 0
	v_cvt_pk_bf16_f32 v5, v30, v31
	v_lshlrev_b32_e32 v30, 16, v176
	v_and_b32_e32 v31, 0xffff0000, v176
	v_pk_fma_f32 v[30:31], v[20:21], v[30:31], 0 op_sel_hi:[0,1,0]
	v_lshlrev_b32_e32 v32, 16, v180
	v_and_b32_e32 v33, 0xffff0000, v180
	v_pk_fma_f32 v[30:31], v[26:27], v[32:33], v[30:31] op_sel_hi:[0,1,1]
	v_lshlrev_b32_e32 v32, 16, v184
	v_and_b32_e32 v33, 0xffff0000, v184
	v_pk_fma_f32 v[30:31], v[18:19], v[32:33], v[30:31] op_sel_hi:[0,1,1]
	v_pk_mul_f32 v[30:31], v[30:31], v[2:3] op_sel_hi:[1,0]
	s_nop 0
	v_cvt_pk_bf16_f32 v6, v30, v31
	v_lshlrev_b32_e32 v30, 16, v177
	v_and_b32_e32 v31, 0xffff0000, v177
	v_pk_fma_f32 v[30:31], v[20:21], v[30:31], 0 op_sel_hi:[0,1,0]
	v_lshlrev_b32_e32 v32, 16, v181
	v_and_b32_e32 v33, 0xffff0000, v181
	v_pk_fma_f32 v[30:31], v[26:27], v[32:33], v[30:31] op_sel_hi:[0,1,1]
	v_lshlrev_b32_e32 v32, 16, v185
	v_and_b32_e32 v33, 0xffff0000, v185
	v_pk_fma_f32 v[30:31], v[18:19], v[32:33], v[30:31] op_sel_hi:[0,1,1]
	v_pk_mul_f32 v[30:31], v[30:31], v[2:3] op_sel_hi:[1,0]
	s_nop 0
	v_cvt_pk_bf16_f32 v7, v30, v31
	v_mad_i64_i32 v[8:9], s[4:5], v196, s71, v[14:15]
	global_store_dwordx4 v[8:9], v[4:7], off
	s_add_i32 s16, s17, s24
	v_add_u32_e32 v23, s24, v189
	s_cmp_lt_i32 s16, s23
	s_cbranch_scc1 .Ldm_trip
.Ldm_done:
	s_or_b64 exec, exec, s[18:19]
; #define LAS __attribute__((address_space(3)))
; DI void phase_gdn_out(KArgs args, LAS unsigned char* L, const Ctx& c) {
;     ...
;     const int lane = c.lane, wave = c.wave, tid = c.tid, l = c.layer;
;     const bf16_t* PROJ = BIGP(bf16_t, B_PROJ); unsigned char* GS = BIGP(unsigned char, B_GSCR); bf16_t* OG = BIGP(bf16_t, B_ONA) + 384;
;     LAS float* OF = (LAS float*)L;
;     const int NU = (c.stok >> 6) * 6; const int dir = wave >> 2, mt = (wave >> 1) & 1, nt = wave & 1, rr = lane & 31, hh = lane >> 5;
;     const float* nw = args->in[7] + l * 64 + 8 * (tid & 7); const f32x4 nw0 = *(const f32x4*)nw, nw1 = *(const f32x4*)(nw + 4);
;     bf16x8 qa[4], sb_[4]; u32x4 oc0, oc1, zw;
;     ...
;     if (c.bid < NU) GOUT_LOAD(c.bid);
.LBB0_1003:
	s_or_b64 exec, exec, s[0:1]
	v_readlane_b32 s0, v254, 23
	v_readlane_b32 s1, v254, 24
	s_and_b64 s[0:1], s[0:1], exec
	s_cselect_b32 s12, 0xc00, s71
	s_cmp_ge_i32 s21, s12
	s_cbranch_scc1 .LBB0_1006
	s_ashr_i32 s18, s22, 6
	s_waitcnt lgkmcnt(0)
	s_add_u32 s0, s2, 0x18200000
	s_addc_u32 s1, s3, 0
	s_add_u32 s13, s2, 0x37800000
	s_addc_u32 s14, s3, 0
	s_add_u32 s2, s2, 0x32600300
	s_mul_hi_i32 s4, s21, 0x2aaaaaab
	s_addc_u32 s3, s3, 0
	s_lshr_b32 s5, s4, 31
	s_add_i32 s16, s4, s5
	s_mul_i32 s4, s16, 6
	s_ashr_i32 s15, s22, 8
	s_sub_i32 s23, s21, s4
	s_lshl_b32 s4, s21, 1
	s_add_i32 s4, s4, s15
	s_and_b32 s19, s18, 1
	s_bfe_u32 s22, s18, 0x10001
	s_mul_hi_i32 s5, s4, 0xa100
	s_mul_i32 s4, s4, 0xa100
	s_add_u32 s10, s13, s4
	s_addc_u32 s11, s14, s5
	s_add_u32 s4, s10, 0x4000
	s_addc_u32 s5, s11, 0
	s_add_u32 s8, s10, 0x8000
	s_addc_u32 s9, s11, 0
	s_add_u32 s10, s10, 0x6000
	s_brev_b32 s17, s18
	s_addc_u32 s11, s11, 0
	s_lshr_b32 s17, s17, 23
	v_and_b32_e32 v2, 63, v1
	s_and_b32 s17, s17, 0x180
	v_or_b32_e32 v66, s17, v2
	s_ashr_i32 s17, s16, 31
	v_ashrrev_i32_e32 v116, 3, v1
	v_lshlrev_b32_e32 v4, 4, v2
	s_lshl_b64 s[16:17], s[16:17], 6
	v_ashrrev_i32_e32 v117, 31, v116
	v_lshl_or_b32 v108, s22, 12, v4
	v_lshl_add_u64 v[4:5], s[16:17], 0, v[116:117]
	v_mov_b64_e32 v[6:7], s[0:1]
	v_mad_u64_u32 v[6:7], s[16:17], v4, s90, v[6:7]
	s_lshl_b32 s16, s23, 6
	v_and_b32_e32 v12, 56, v22
	v_mad_i32_i24 v7, v5, s90, v7
	s_ashr_i32 s17, s16, 31
	v_lshl_or_b32 v14, s19, 8, v2
	v_lshl_add_u64 v[4:5], s[16:17], 1, v[6:7]
	v_lshlrev_b32_e32 v2, 1, v12
	s_lshl_b32 s16, s22, 5
	v_lshrrev_b32_e32 v1, 3, v1
	v_lshl_add_u64 v[28:29], v[4:5], 0, v[2:3]
	v_and_b32_e32 v2, 4, v1
	s_cmp_lt_u32 s18, 4
	v_or_b32_e32 v4, s16, v2
	s_cselect_b64 vcc, -1, 0
	s_lshl_b32 s18, s19, 7
	v_bitop3_b32 v6, s16, 63, v2 bitop3:0x36
	s_lshl_b32 s17, s15, 6
	s_add_i32 s18, s18, 0
	v_cndmask_b32_e32 v6, v6, v4, vcc
	v_lshl_add_u32 v13, v21, 2, s18
	s_movk_i32 s18, 0x110
	v_or_b32_e32 v6, s17, v6
	v_mul_lo_u32 v15, v6, s18
	v_or_b32_e32 v6, 1, v4
	v_bitop3_b32 v7, s16, 62, v2 bitop3:0x36
	v_cndmask_b32_e32 v6, v7, v6, vcc
	v_or_b32_e32 v6, s17, v6
	v_mul_lo_u32 v17, v6, s18
	v_or_b32_e32 v6, 2, v4
	v_bitop3_b32 v7, s16, 61, v2 bitop3:0x36
	v_cndmask_b32_e32 v6, v7, v6, vcc
	v_or_b32_e32 v6, s17, v6
	v_mul_lo_u32 v19, v6, s18
	v_or_b32_e32 v6, 3, v4
	v_bitop3_b32 v7, s16, 60, v2 bitop3:0x36
	v_cndmask_b32_e32 v6, v7, v6, vcc
	v_or_b32_e32 v6, s17, v6
	v_mul_lo_u32 v65, v6, s18
	v_or_b32_e32 v6, 8, v4
	v_bitop3_b32 v7, s16, 55, v2 bitop3:0x36
	v_cndmask_b32_e32 v6, v7, v6, vcc
	v_or_b32_e32 v6, s17, v6
	v_mul_lo_u32 v67, v6, s18
	v_or_b32_e32 v6, 9, v4
	v_bitop3_b32 v7, s16, 54, v2 bitop3:0x36
	v_cndmask_b32_e32 v6, v7, v6, vcc
	v_or_b32_e32 v6, s17, v6
	v_mul_lo_u32 v69, v6, s18
	v_or_b32_e32 v6, 10, v4
	v_bitop3_b32 v7, s16, 53, v2 bitop3:0x36
	v_cndmask_b32_e32 v6, v7, v6, vcc
	v_or_b32_e32 v6, s17, v6
	v_mul_lo_u32 v70, v6, s18
	v_or_b32_e32 v6, 11, v4
	v_bitop3_b32 v7, s16, 52, v2 bitop3:0x36
	v_cndmask_b32_e32 v6, v7, v6, vcc
	v_or_b32_e32 v6, s17, v6
	v_mul_lo_u32 v71, v6, s18
	v_or_b32_e32 v6, 16, v4
	v_bitop3_b32 v7, s16, 47, v2 bitop3:0x36
	v_cndmask_b32_e32 v6, v7, v6, vcc
	v_or_b32_e32 v6, s17, v6
	v_mul_lo_u32 v72, v6, s18
	v_or_b32_e32 v6, 17, v4
	v_bitop3_b32 v7, s16, 46, v2 bitop3:0x36
	v_cndmask_b32_e32 v6, v7, v6, vcc
	v_or_b32_e32 v6, s17, v6
	v_mul_lo_u32 v73, v6, s18
	v_or_b32_e32 v6, 18, v4
	v_bitop3_b32 v7, s16, 45, v2 bitop3:0x36
	v_cndmask_b32_e32 v6, v7, v6, vcc
	v_or_b32_e32 v6, s17, v6
	v_mul_lo_u32 v74, v6, s18
	v_or_b32_e32 v6, 19, v4
	v_bitop3_b32 v7, s16, 44, v2 bitop3:0x36
	v_cndmask_b32_e32 v6, v7, v6, vcc
	v_or_b32_e32 v6, s17, v6
	v_mul_lo_u32 v75, v6, s18
	v_or_b32_e32 v6, 24, v4
	v_bitop3_b32 v7, s16, 39, v2 bitop3:0x36
	v_cndmask_b32_e32 v6, v7, v6, vcc
	v_or_b32_e32 v6, s17, v6
	v_mul_lo_u32 v76, v6, s18
	v_or_b32_e32 v6, 25, v4
	v_bitop3_b32 v7, s16, 38, v2 bitop3:0x36
	v_cndmask_b32_e32 v6, v7, v6, vcc
	s_load_dwordx2 s[6:7], s[6:7], 0x38
	v_or_b32_e32 v6, s17, v6
	v_mul_lo_u32 v77, v6, s18
	v_or_b32_e32 v6, 26, v4
	v_bitop3_b32 v7, s16, 37, v2 bitop3:0x36
	v_or_b32_e32 v4, 27, v4
	v_bitop3_b32 v2, s16, 36, v2 bitop3:0x36
	v_cndmask_b32_e32 v6, v7, v6, vcc
	v_cndmask_b32_e32 v2, v2, v4, vcc
	v_or_b32_e32 v6, s17, v6
	v_or_b32_e32 v2, s17, v2
	v_readlane_b32 s16, v254, 21
	v_or_b32_e32 v18, 0x80, v14
	v_or_b32_e32 v64, 0xc0, v14
	v_or_b32_e32 v68, 64, v66
	v_readlane_b32 s17, v254, 22
	s_waitcnt lgkmcnt(0)
	s_add_u32 s6, s6, s16
	v_or_b32_e32 v16, 64, v14
	v_lshlrev_b32_e32 v32, 4, v18
	v_lshlrev_b32_e32 v33, 4, v64
	v_lshlrev_b32_e32 v34, 4, v66
	v_lshlrev_b32_e32 v35, 4, v68
	v_mul_lo_u32 v1, v116, s18
	v_lshlrev_b32_e32 v5, 2, v12
	s_addc_u32 s7, s7, s17
	v_lshlrev_b32_e32 v30, 4, v14
	v_or_b32_e32 v110, 0x400, v108
	v_lshlrev_b32_e32 v31, 4, v16
	v_or_b32_e32 v112, 0x800, v108
	v_or_b32_e32 v114, 0xc00, v108
	v_add3_u32 v1, 0, v1, v5
	v_mul_lo_u32 v78, v6, s18
	global_load_dwordx4 v[20:23], v5, s[6:7]
	global_load_dwordx4 v[24:27], v5, s[6:7] offset:16
	global_load_dwordx4 v[8:11], v108, s[4:5]
	s_nop 0
	global_load_dwordx4 v[4:7], v30, s[8:9]
	global_load_dwordx4 v[52:55], v110, s[4:5]
	global_load_dwordx4 v[40:43], v31, s[8:9]
	global_load_dwordx4 v[56:59], v112, s[4:5]
	global_load_dwordx4 v[44:47], v32, s[8:9]
	global_load_dwordx4 v[60:63], v114, s[4:5]
	global_load_dwordx4 v[48:51], v33, s[8:9]
	global_load_dwordx4 v[36:39], v34, s[10:11]
	s_nop 0
	global_load_dwordx4 v[32:35], v35, s[10:11]
	v_add_co_u32_e32 v28, vcc, s70, v28
	v_mul_lo_u32 v79, v2, s18
	s_nop 0
	v_addc_co_u32_e32 v29, vcc, 0, v29, vcc
	global_load_dwordx4 v[28:31], v[28:29], off offset:2048
	v_mov_b32_e32 v109, v3
	v_mov_b32_e32 v111, v3
	v_mov_b32_e32 v113, v3
	v_mov_b32_e32 v115, v3
	s_lshl_b32 s10, s21, 6
	s_lshl_b32 s11, s20, 6
	v_lshlrev_b32_e32 v118, 4, v14
	v_lshlrev_b32_e32 v119, 4, v16
	v_lshlrev_b32_e32 v120, 4, v18
	v_lshlrev_b32_e32 v121, 4, v64
	v_lshlrev_b32_e32 v122, 4, v66
	v_lshlrev_b32_e32 v123, 4, v68
	v_lshlrev_b32_e32 v2, 1, v12
	v_add_u32_e32 v124, v13, v15
	v_add_u32_e32 v125, v13, v17
	v_add_u32_e32 v126, v13, v19
	v_add_u32_e32 v127, v13, v65
	v_add_u32_e32 v128, v13, v67
	v_add_u32_e32 v129, v13, v69
	v_add_u32_e32 v130, v13, v70
	v_add_u32_e32 v131, v13, v71
	v_add_u32_e32 v132, v13, v72
	v_add_u32_e32 v133, v13, v73
	v_add_u32_e32 v134, v13, v74
	v_add_u32_e32 v135, v13, v75
	v_add_u32_e32 v136, v13, v76
	v_add_u32_e32 v137, v13, v77
	v_add_u32_e32 v138, v13, v78
	v_add_u32_e32 v139, v13, v79
